# plus prep fold item: the eight w_up_pool row loads issued together with one wait instead of four serialized pairs
# speedup vs baseline: 1.0171x; 1.0171x over previous
; #define LAS __attribute__((address_space(3)))
; __device__ __forceinline__ void prep_phase(const Params& p, int l, LAS unsigned char* lds) {
;     ...
;         if (r < I_PP) {
;             const int g = r >> 9, d0 = ((r >> 1) & 255) * 4, cblk = r & 1; const int c = cblk * 64 + lane;
;             const float* pwr = pw + (size_t)(g * 128 + c) * 128; const float* psg = ps + g * 128; const float* wu = wup + (size_t)(g * 128) * D + d0;
;             f32x4 pwv[32];
; #pragma unroll
;             for (int jj = 0; jj < 32; ++jj) pwv[jj] = *(const f32x4*)(pwr + 4 * jj);
; #pragma unroll
;             for (int i = 0; i < 8; ++i) { const int idx = i * 64 + lane; scr[idx] = wu[(size_t)(idx >> 2) * D + (idx & 3)]; }
;             asm volatile("s_waitcnt lgkmcnt(0)" ::: "memory");
;             f32x4 acc = {0.f, 0.f, 0.f, 0.f};
; #pragma unroll
;             for (int jj = 0; jj < 32; ++jj) { const f32x4 a4 = pwv[jj] * *(const f32x4*)(psg + 4 * jj);
; #pragma unroll
;                 for (int t = 0; t < 4; ++t) acc += *(const LAS f32x4*)(scr + (4 * jj + t) * 4) * a4[t]; }
.LBB0_47:
	s_andn2_b64 vcc, exec, s[0:1]
	s_cbranch_vccnz .LBB0_16
	s_ashr_i32 s0, s22, 2
	s_and_b32 s54, s0, 0xffffff80
	s_ashr_i32 s55, s54, 31
	s_and_b32 s12, s18, 0x3fc
	v_and_or_b32 v112, s21, 64, v131
	s_lshl_b64 s[0:1], s[54:55], 12
	v_or_b32_e32 v0, s54, v112
	s_add_u32 s0, s11, s0
	v_ashrrev_i32_e32 v1, 31, v0
	s_addc_u32 s1, s14, s1
	s_lshl_b32 s13, s12, 2
	v_lshlrev_b64 v[0:1], 9, v[0:1]
	s_add_u32 s0, s0, s13
	v_lshl_add_u64 v[12:13], s[50:51], 0, v[0:1]
	s_addc_u32 s1, s1, 0
	global_load_dwordx4 v[114:117], v[12:13], off offset:48
	global_load_dwordx4 v[118:121], v[12:13], off offset:32
	global_load_dwordx4 v[122:125], v[12:13], off offset:16
	global_load_dwordx4 v[126:129], v[12:13], off
	global_load_dwordx4 v[96:99], v[12:13], off offset:112
	global_load_dwordx4 v[100:103], v[12:13], off offset:96
	global_load_dwordx4 v[104:107], v[12:13], off offset:80
	global_load_dwordx4 v[108:111], v[12:13], off offset:64
	global_load_dwordx4 v[80:83], v[12:13], off offset:176
	global_load_dwordx4 v[84:87], v[12:13], off offset:160
	global_load_dwordx4 v[88:91], v[12:13], off offset:144
	global_load_dwordx4 v[92:95], v[12:13], off offset:128
	global_load_dwordx4 v[64:67], v[12:13], off offset:240
	global_load_dwordx4 v[68:71], v[12:13], off offset:224
	global_load_dwordx4 v[72:75], v[12:13], off offset:208
	global_load_dwordx4 v[76:79], v[12:13], off offset:192
	global_load_dwordx4 v[48:51], v[12:13], off offset:304
	global_load_dwordx4 v[52:55], v[12:13], off offset:288
	global_load_dwordx4 v[56:59], v[12:13], off offset:272
	global_load_dwordx4 v[60:63], v[12:13], off offset:256
	global_load_dwordx4 v[32:35], v[12:13], off offset:368
	global_load_dwordx4 v[36:39], v[12:13], off offset:352
	global_load_dwordx4 v[40:43], v[12:13], off offset:336
	global_load_dwordx4 v[44:47], v[12:13], off offset:320
	global_load_dwordx4 v[16:19], v[12:13], off offset:432
	global_load_dwordx4 v[20:23], v[12:13], off offset:416
	global_load_dwordx4 v[24:27], v[12:13], off offset:400
	global_load_dwordx4 v[28:31], v[12:13], off offset:384
	global_load_dwordx4 v[0:3], v[12:13], off offset:496
	global_load_dwordx4 v[4:7], v[12:13], off offset:480
	global_load_dwordx4 v[8:11], v[12:13], off offset:464
	s_nop 0
	global_load_dwordx4 v[12:15], v[12:13], off offset:448
	s_nop 0
	global_load_dword v240, v150, s[0:1]
	global_load_dword v241, v151, s[0:1]
	global_load_dword v242, v152, s[0:1]
	global_load_dword v243, v153, s[0:1]
	global_load_dword v244, v154, s[0:1]
	global_load_dword v245, v155, s[0:1]
	global_load_dword v246, v156, s[0:1]
	global_load_dword v247, v157, s[0:1]
	v_lshlrev_b32_e32 v112, 1, v112
	s_lshl_b64 s[0:1], s[54:55], 2
	s_add_u32 s62, s15, s0
	s_addc_u32 s63, s16, s1
	s_waitcnt vmcnt(0)
	ds_write2st64_b32 v149, v240, v241 offset1:1
	ds_write2st64_b32 v149, v242, v243 offset0:2 offset1:3
	ds_write2st64_b32 v149, v244, v245 offset0:4 offset1:5
	ds_write2st64_b32 v149, v246, v247 offset0:6 offset1:7
	s_waitcnt lgkmcnt(0)
	global_load_dwordx4 v[166:169], v113, s[62:63] offset:48
	global_load_dwordx4 v[170:173], v113, s[62:63] offset:32
	global_load_dwordx4 v[174:177], v113, s[62:63] offset:16
	global_load_dwordx4 v[178:181], v113, s[62:63]
	v_mov_b32_e32 v139, s3
	ds_read_b128 v[200:203], v139
	ds_read_b128 v[204:207], v139 offset:16
	ds_read_b128 v[208:211], v139 offset:32
	ds_read_b128 v[222:225], v139 offset:48
	s_waitcnt vmcnt(3)
	v_mul_f32_e32 v114, v114, v166
	s_waitcnt vmcnt(2)
	v_mul_f32_e32 v118, v118, v170
	s_waitcnt vmcnt(1)
	v_mul_f32_e32 v122, v122, v174
	s_waitcnt vmcnt(0)
	v_mul_f32_e32 v126, v126, v178
	s_waitcnt lgkmcnt(3)
	v_pk_fma_f32 v[184:185], v[200:201], v[126:127], 0 op_sel_hi:[1,0,0]
	v_pk_fma_f32 v[186:187], v[202:203], v[126:127], 0 op_sel_hi:[1,0,0]
	v_mul_f32_e32 v126, v127, v179
	s_waitcnt lgkmcnt(2)
	v_pk_fma_f32 v[178:179], v[206:207], v[126:127], v[186:187] op_sel_hi:[1,0,1]
	v_pk_fma_f32 v[126:127], v[204:205], v[126:127], v[184:185] op_sel_hi:[1,0,1]
	v_mul_f32_e32 v128, v128, v180
	s_waitcnt lgkmcnt(1)
	v_pk_fma_f32 v[126:127], v[208:209], v[128:129], v[126:127] op_sel_hi:[1,0,1]
	v_pk_fma_f32 v[178:179], v[210:211], v[128:129], v[178:179] op_sel_hi:[1,0,1]
	v_mul_f32_e32 v128, v129, v181
	s_waitcnt lgkmcnt(0)
	v_pk_fma_f32 v[178:179], v[128:129], v[224:225], v[178:179] op_sel_hi:[0,1,1]
	v_pk_fma_f32 v[180:181], v[128:129], v[222:223], v[126:127] op_sel_hi:[0,1,1]
	ds_read_b128 v[126:129], v139 offset:64
	v_mul_f32_e32 v124, v124, v176
	v_mul_f32_e32 v120, v120, v172
	v_mul_f32_e32 v116, v116, v168
	s_waitcnt lgkmcnt(0)
	v_pk_fma_f32 v[180:181], v[126:127], v[122:123], v[180:181] op_sel_hi:[1,0,1]
	v_pk_fma_f32 v[178:179], v[128:129], v[122:123], v[178:179] op_sel_hi:[1,0,1]
	ds_read_b128 v[126:129], v139 offset:80
	v_mul_f32_e32 v122, v123, v175
	s_waitcnt lgkmcnt(0)
	v_pk_fma_f32 v[174:175], v[128:129], v[122:123], v[178:179] op_sel_hi:[1,0,1]
	v_pk_fma_f32 v[122:123], v[126:127], v[122:123], v[180:181] op_sel_hi:[1,0,1]
	ds_read_b128 v[126:129], v139 offset:96
	s_waitcnt lgkmcnt(0)
	v_pk_fma_f32 v[122:123], v[126:127], v[124:125], v[122:123] op_sel_hi:[1,0,1]
	v_pk_fma_f32 v[174:175], v[128:129], v[124:125], v[174:175] op_sel_hi:[1,0,1]
	ds_read_b128 v[126:129], v139 offset:112
	v_mul_f32_e32 v124, v125, v177
	s_waitcnt lgkmcnt(0)
	v_pk_fma_f32 v[128:129], v[124:125], v[128:129], v[174:175] op_sel_hi:[0,1,1]
	v_pk_fma_f32 v[126:127], v[124:125], v[126:127], v[122:123] op_sel_hi:[0,1,1]
	ds_read_b128 v[122:125], v139 offset:128
	s_waitcnt lgkmcnt(0)
	v_pk_fma_f32 v[126:127], v[122:123], v[118:119], v[126:127] op_sel_hi:[1,0,1]
	v_pk_fma_f32 v[128:129], v[124:125], v[118:119], v[128:129] op_sel_hi:[1,0,1]
	ds_read_b128 v[122:125], v139 offset:144
	v_mul_f32_e32 v118, v119, v171
	s_waitcnt lgkmcnt(0)
; #define LAS __attribute__((address_space(3)))
; __device__ __forceinline__ void prep_phase(const Params& p, int l, LAS unsigned char* lds) {
;     ...
;             for (int jj = 0; jj < 32; ++jj) { const f32x4 a4 = pwv[jj] * *(const f32x4*)(psg + 4 * jj);
; #pragma unroll
;                 for (int t = 0; t < 4; ++t) acc += *(const LAS f32x4*)(scr + (4 * jj + t) * 4) * a4[t]; }
	v_pk_fma_f32 v[128:129], v[124:125], v[118:119], v[128:129] op_sel_hi:[1,0,1]
	v_pk_fma_f32 v[118:119], v[122:123], v[118:119], v[126:127] op_sel_hi:[1,0,1]
	ds_read_b128 v[122:125], v139 offset:160
	s_waitcnt lgkmcnt(0)
	v_pk_fma_f32 v[118:119], v[122:123], v[120:121], v[118:119] op_sel_hi:[1,0,1]
	v_pk_fma_f32 v[126:127], v[124:125], v[120:121], v[128:129] op_sel_hi:[1,0,1]
	ds_read_b128 v[122:125], v139 offset:176
	v_mul_f32_e32 v120, v121, v173
	s_waitcnt lgkmcnt(0)
	v_pk_fma_f32 v[124:125], v[120:121], v[124:125], v[126:127] op_sel_hi:[0,1,1]
	v_pk_fma_f32 v[122:123], v[120:121], v[122:123], v[118:119] op_sel_hi:[0,1,1]
	ds_read_b128 v[118:121], v139 offset:192
	s_waitcnt lgkmcnt(0)
	v_pk_fma_f32 v[122:123], v[118:119], v[114:115], v[122:123] op_sel_hi:[1,0,1]
	v_pk_fma_f32 v[124:125], v[120:121], v[114:115], v[124:125] op_sel_hi:[1,0,1]
	ds_read_b128 v[118:121], v139 offset:208
	v_mul_f32_e32 v114, v115, v167
	s_waitcnt lgkmcnt(0)
	v_pk_fma_f32 v[124:125], v[120:121], v[114:115], v[124:125] op_sel_hi:[1,0,1]
	v_pk_fma_f32 v[114:115], v[118:119], v[114:115], v[122:123] op_sel_hi:[1,0,1]
	ds_read_b128 v[118:121], v139 offset:224
	s_waitcnt lgkmcnt(0)
	v_pk_fma_f32 v[114:115], v[118:119], v[116:117], v[114:115] op_sel_hi:[1,0,1]
	v_pk_fma_f32 v[122:123], v[120:121], v[116:117], v[124:125] op_sel_hi:[1,0,1]
	ds_read_b128 v[118:121], v139 offset:240
	v_mul_f32_e32 v116, v117, v169
	s_waitcnt lgkmcnt(0)
	v_pk_fma_f32 v[126:127], v[116:117], v[120:121], v[122:123] op_sel_hi:[0,1,1]
	v_pk_fma_f32 v[128:129], v[116:117], v[118:119], v[114:115] op_sel_hi:[0,1,1]
	global_load_dwordx4 v[114:117], v113, s[62:63] offset:112
	global_load_dwordx4 v[118:121], v113, s[62:63] offset:96
	global_load_dwordx4 v[122:125], v113, s[62:63] offset:80
	global_load_dwordx4 v[166:169], v113, s[62:63] offset:64
	ds_read_b128 v[170:173], v139 offset:256
	s_waitcnt vmcnt(3)
	v_mul_f32_e32 v96, v96, v114
	s_waitcnt vmcnt(2)
	v_mul_f32_e32 v100, v100, v118
	s_waitcnt vmcnt(1)
	v_mul_f32_e32 v104, v104, v122
	s_waitcnt vmcnt(0)
	v_mul_f32_e32 v108, v108, v166
	s_waitcnt lgkmcnt(0)
	v_pk_fma_f32 v[170:171], v[170:171], v[108:109], v[128:129] op_sel_hi:[1,0,1]
	v_pk_fma_f32 v[172:173], v[172:173], v[108:109], v[126:127] op_sel_hi:[1,0,1]
	ds_read_b128 v[126:129], v139 offset:272
	v_mul_f32_e32 v108, v109, v167
	v_mul_f32_e32 v110, v110, v168
	v_mul_f32_e32 v106, v106, v124
	v_mul_f32_e32 v102, v102, v120
	s_waitcnt lgkmcnt(0)
	v_pk_fma_f32 v[166:167], v[128:129], v[108:109], v[172:173] op_sel_hi:[1,0,1]
	v_pk_fma_f32 v[108:109], v[126:127], v[108:109], v[170:171] op_sel_hi:[1,0,1]
	ds_read_b128 v[126:129], v139 offset:288
	v_mul_f32_e32 v98, v98, v116
	s_waitcnt lgkmcnt(0)
	v_pk_fma_f32 v[108:109], v[126:127], v[110:111], v[108:109] op_sel_hi:[1,0,1]
	v_pk_fma_f32 v[166:167], v[128:129], v[110:111], v[166:167] op_sel_hi:[1,0,1]
	ds_read_b128 v[126:129], v139 offset:304
	v_mul_f32_e32 v110, v111, v169
	s_waitcnt lgkmcnt(0)
	v_pk_fma_f32 v[128:129], v[110:111], v[128:129], v[166:167] op_sel_hi:[0,1,1]
	v_pk_fma_f32 v[126:127], v[110:111], v[126:127], v[108:109] op_sel_hi:[0,1,1]
	ds_read_b128 v[108:111], v139 offset:320
	s_waitcnt lgkmcnt(0)
	v_pk_fma_f32 v[126:127], v[108:109], v[104:105], v[126:127] op_sel_hi:[1,0,1]
	v_pk_fma_f32 v[128:129], v[110:111], v[104:105], v[128:129] op_sel_hi:[1,0,1]
	ds_read_b128 v[108:111], v139 offset:336
	v_mul_f32_e32 v104, v105, v123
	s_waitcnt lgkmcnt(0)
	v_pk_fma_f32 v[122:123], v[110:111], v[104:105], v[128:129] op_sel_hi:[1,0,1]
	v_pk_fma_f32 v[104:105], v[108:109], v[104:105], v[126:127] op_sel_hi:[1,0,1]
	ds_read_b128 v[108:111], v139 offset:352
	s_waitcnt lgkmcnt(0)
	v_pk_fma_f32 v[104:105], v[108:109], v[106:107], v[104:105] op_sel_hi:[1,0,1]
	v_pk_fma_f32 v[122:123], v[110:111], v[106:107], v[122:123] op_sel_hi:[1,0,1]
	ds_read_b128 v[108:111], v139 offset:368
	v_mul_f32_e32 v106, v107, v125
	s_waitcnt lgkmcnt(0)
	v_pk_fma_f32 v[110:111], v[106:107], v[110:111], v[122:123] op_sel_hi:[0,1,1]
	v_pk_fma_f32 v[108:109], v[106:107], v[108:109], v[104:105] op_sel_hi:[0,1,1]
	ds_read_b128 v[104:107], v139 offset:384
	s_waitcnt lgkmcnt(0)
	v_pk_fma_f32 v[108:109], v[104:105], v[100:101], v[108:109] op_sel_hi:[1,0,1]
	v_pk_fma_f32 v[110:111], v[106:107], v[100:101], v[110:111] op_sel_hi:[1,0,1]
	ds_read_b128 v[104:107], v139 offset:400
	v_mul_f32_e32 v100, v101, v119
	s_waitcnt lgkmcnt(0)
	v_pk_fma_f32 v[110:111], v[106:107], v[100:101], v[110:111] op_sel_hi:[1,0,1]
	v_pk_fma_f32 v[100:101], v[104:105], v[100:101], v[108:109] op_sel_hi:[1,0,1]
	ds_read_b128 v[104:107], v139 offset:416
	s_waitcnt lgkmcnt(0)
	v_pk_fma_f32 v[100:101], v[104:105], v[102:103], v[100:101] op_sel_hi:[1,0,1]
	v_pk_fma_f32 v[108:109], v[106:107], v[102:103], v[110:111] op_sel_hi:[1,0,1]
	ds_read_b128 v[104:107], v139 offset:432
	v_mul_f32_e32 v102, v103, v121
	s_waitcnt lgkmcnt(0)
	v_pk_fma_f32 v[106:107], v[102:103], v[106:107], v[108:109] op_sel_hi:[0,1,1]
	v_pk_fma_f32 v[104:105], v[102:103], v[104:105], v[100:101] op_sel_hi:[0,1,1]
	ds_read_b128 v[100:103], v139 offset:448
	s_waitcnt lgkmcnt(0)
	v_pk_fma_f32 v[104:105], v[100:101], v[96:97], v[104:105] op_sel_hi:[1,0,1]
	v_pk_fma_f32 v[106:107], v[102:103], v[96:97], v[106:107] op_sel_hi:[1,0,1]
	ds_read_b128 v[100:103], v139 offset:464
	v_mul_f32_e32 v96, v97, v115
	s_waitcnt lgkmcnt(0)
	v_pk_fma_f32 v[106:107], v[102:103], v[96:97], v[106:107] op_sel_hi:[1,0,1]
	v_pk_fma_f32 v[96:97], v[100:101], v[96:97], v[104:105] op_sel_hi:[1,0,1]
	ds_read_b128 v[100:103], v139 offset:480
	s_waitcnt lgkmcnt(0)
; #define LAS __attribute__((address_space(3)))
; __device__ __forceinline__ void prep_phase(const Params& p, int l, LAS unsigned char* lds) {
;     ...
;             for (int jj = 0; jj < 32; ++jj) { const f32x4 a4 = pwv[jj] * *(const f32x4*)(psg + 4 * jj);
; #pragma unroll
;                 for (int t = 0; t < 4; ++t) acc += *(const LAS f32x4*)(scr + (4 * jj + t) * 4) * a4[t]; }
	v_pk_fma_f32 v[96:97], v[100:101], v[98:99], v[96:97] op_sel_hi:[1,0,1]
	v_pk_fma_f32 v[104:105], v[102:103], v[98:99], v[106:107] op_sel_hi:[1,0,1]
	ds_read_b128 v[100:103], v139 offset:496
	v_mul_f32_e32 v98, v99, v117
	s_waitcnt lgkmcnt(0)
	v_pk_fma_f32 v[118:119], v[98:99], v[102:103], v[104:105] op_sel_hi:[0,1,1]
	v_pk_fma_f32 v[120:121], v[98:99], v[100:101], v[96:97] op_sel_hi:[0,1,1]
	global_load_dwordx4 v[96:99], v113, s[62:63] offset:176
	global_load_dwordx4 v[100:103], v113, s[62:63] offset:160
	global_load_dwordx4 v[104:107], v113, s[62:63] offset:144
	global_load_dwordx4 v[108:111], v113, s[62:63] offset:128
	ds_read_b128 v[114:117], v139 offset:512
	s_waitcnt vmcnt(3)
	v_mul_f32_e32 v80, v80, v96
	s_waitcnt vmcnt(2)
	v_mul_f32_e32 v84, v84, v100
	s_waitcnt vmcnt(1)
	v_mul_f32_e32 v88, v88, v104
	s_waitcnt vmcnt(0)
	v_mul_f32_e32 v92, v92, v108
	s_waitcnt lgkmcnt(0)
	v_pk_fma_f32 v[120:121], v[114:115], v[92:93], v[120:121] op_sel_hi:[1,0,1]
	v_pk_fma_f32 v[118:119], v[116:117], v[92:93], v[118:119] op_sel_hi:[1,0,1]
	ds_read_b128 v[114:117], v139 offset:528
	v_mul_f32_e32 v92, v93, v109
	v_mul_f32_e32 v94, v94, v110
	v_mul_f32_e32 v90, v90, v106
	v_mul_f32_e32 v86, v86, v102
	s_waitcnt lgkmcnt(0)
	v_pk_fma_f32 v[108:109], v[116:117], v[92:93], v[118:119] op_sel_hi:[1,0,1]
	v_pk_fma_f32 v[92:93], v[114:115], v[92:93], v[120:121] op_sel_hi:[1,0,1]
	ds_read_b128 v[114:117], v139 offset:544
	v_mul_f32_e32 v82, v82, v98
	s_waitcnt lgkmcnt(0)
	v_pk_fma_f32 v[92:93], v[114:115], v[94:95], v[92:93] op_sel_hi:[1,0,1]
	v_pk_fma_f32 v[108:109], v[116:117], v[94:95], v[108:109] op_sel_hi:[1,0,1]
	ds_read_b128 v[114:117], v139 offset:560
	v_mul_f32_e32 v94, v95, v111
	s_waitcnt lgkmcnt(0)
	v_pk_fma_f32 v[108:109], v[94:95], v[116:117], v[108:109] op_sel_hi:[0,1,1]
	v_pk_fma_f32 v[110:111], v[94:95], v[114:115], v[92:93] op_sel_hi:[0,1,1]
	ds_read_b128 v[92:95], v139 offset:576
	s_waitcnt lgkmcnt(0)
	v_pk_fma_f32 v[110:111], v[92:93], v[88:89], v[110:111] op_sel_hi:[1,0,1]
	v_pk_fma_f32 v[108:109], v[94:95], v[88:89], v[108:109] op_sel_hi:[1,0,1]
	ds_read_b128 v[92:95], v139 offset:592
	v_mul_f32_e32 v88, v89, v105
	s_waitcnt lgkmcnt(0)
	v_pk_fma_f32 v[104:105], v[94:95], v[88:89], v[108:109] op_sel_hi:[1,0,1]
	v_pk_fma_f32 v[88:89], v[92:93], v[88:89], v[110:111] op_sel_hi:[1,0,1]
	ds_read_b128 v[92:95], v139 offset:608
	s_waitcnt lgkmcnt(0)
	v_pk_fma_f32 v[88:89], v[92:93], v[90:91], v[88:89] op_sel_hi:[1,0,1]
	v_pk_fma_f32 v[104:105], v[94:95], v[90:91], v[104:105] op_sel_hi:[1,0,1]
	ds_read_b128 v[92:95], v139 offset:624
	v_mul_f32_e32 v90, v91, v107
	s_waitcnt lgkmcnt(0)
	v_pk_fma_f32 v[94:95], v[90:91], v[94:95], v[104:105] op_sel_hi:[0,1,1]
	v_pk_fma_f32 v[92:93], v[90:91], v[92:93], v[88:89] op_sel_hi:[0,1,1]
	ds_read_b128 v[88:91], v139 offset:640
	s_waitcnt lgkmcnt(0)
	v_pk_fma_f32 v[92:93], v[88:89], v[84:85], v[92:93] op_sel_hi:[1,0,1]
	v_pk_fma_f32 v[94:95], v[90:91], v[84:85], v[94:95] op_sel_hi:[1,0,1]
	ds_read_b128 v[88:91], v139 offset:656
	v_mul_f32_e32 v84, v85, v101
	s_waitcnt lgkmcnt(0)
	v_pk_fma_f32 v[94:95], v[90:91], v[84:85], v[94:95] op_sel_hi:[1,0,1]
	v_pk_fma_f32 v[84:85], v[88:89], v[84:85], v[92:93] op_sel_hi:[1,0,1]
	ds_read_b128 v[88:91], v139 offset:672
	s_waitcnt lgkmcnt(0)
	v_pk_fma_f32 v[84:85], v[88:89], v[86:87], v[84:85] op_sel_hi:[1,0,1]
	v_pk_fma_f32 v[92:93], v[90:91], v[86:87], v[94:95] op_sel_hi:[1,0,1]
	ds_read_b128 v[88:91], v139 offset:688
	v_mul_f32_e32 v86, v87, v103
	s_waitcnt lgkmcnt(0)
	v_pk_fma_f32 v[90:91], v[86:87], v[90:91], v[92:93] op_sel_hi:[0,1,1]
	v_pk_fma_f32 v[88:89], v[86:87], v[88:89], v[84:85] op_sel_hi:[0,1,1]
	ds_read_b128 v[84:87], v139 offset:704
	s_waitcnt lgkmcnt(0)
	v_pk_fma_f32 v[88:89], v[84:85], v[80:81], v[88:89] op_sel_hi:[1,0,1]
	v_pk_fma_f32 v[90:91], v[86:87], v[80:81], v[90:91] op_sel_hi:[1,0,1]
	ds_read_b128 v[84:87], v139 offset:720
	v_mul_f32_e32 v80, v81, v97
	s_waitcnt lgkmcnt(0)
	v_pk_fma_f32 v[90:91], v[86:87], v[80:81], v[90:91] op_sel_hi:[1,0,1]
	v_pk_fma_f32 v[80:81], v[84:85], v[80:81], v[88:89] op_sel_hi:[1,0,1]
	ds_read_b128 v[84:87], v139 offset:736
	s_waitcnt lgkmcnt(0)
	v_pk_fma_f32 v[80:81], v[84:85], v[82:83], v[80:81] op_sel_hi:[1,0,1]
	v_pk_fma_f32 v[88:89], v[86:87], v[82:83], v[90:91] op_sel_hi:[1,0,1]
	ds_read_b128 v[84:87], v139 offset:752
	v_mul_f32_e32 v82, v83, v99
	s_waitcnt lgkmcnt(0)
	v_pk_fma_f32 v[88:89], v[82:83], v[86:87], v[88:89] op_sel_hi:[0,1,1]
	v_pk_fma_f32 v[90:91], v[82:83], v[84:85], v[80:81] op_sel_hi:[0,1,1]
	global_load_dwordx4 v[80:83], v113, s[62:63] offset:240
	global_load_dwordx4 v[84:87], v113, s[62:63] offset:224
	global_load_dwordx4 v[92:95], v113, s[62:63] offset:208
	global_load_dwordx4 v[96:99], v113, s[62:63] offset:192
	ds_read_b128 v[100:103], v139 offset:768
	s_waitcnt vmcnt(3)
	v_mul_f32_e32 v64, v64, v80
	s_waitcnt vmcnt(2)
	v_mul_f32_e32 v68, v68, v84
	s_waitcnt vmcnt(1)
	v_mul_f32_e32 v72, v72, v92
	s_waitcnt vmcnt(0)
	v_mul_f32_e32 v76, v76, v96
	s_waitcnt lgkmcnt(0)
	v_pk_fma_f32 v[100:101], v[100:101], v[76:77], v[90:91] op_sel_hi:[1,0,1]
	v_pk_fma_f32 v[102:103], v[102:103], v[76:77], v[88:89] op_sel_hi:[1,0,1]
	ds_read_b128 v[88:91], v139 offset:784
	v_mul_f32_e32 v76, v77, v97
	v_mul_f32_e32 v78, v78, v98
	v_mul_f32_e32 v74, v74, v94
	v_mul_f32_e32 v70, v70, v86
	s_waitcnt lgkmcnt(0)
	v_pk_fma_f32 v[96:97], v[90:91], v[76:77], v[102:103] op_sel_hi:[1,0,1]
	v_pk_fma_f32 v[76:77], v[88:89], v[76:77], v[100:101] op_sel_hi:[1,0,1]
	ds_read_b128 v[88:91], v139 offset:800
	v_mul_f32_e32 v66, v66, v82
	s_waitcnt lgkmcnt(0)
; #define LAS __attribute__((address_space(3)))
; __device__ __forceinline__ void prep_phase(const Params& p, int l, LAS unsigned char* lds) {
;     ...
;             for (int jj = 0; jj < 32; ++jj) { const f32x4 a4 = pwv[jj] * *(const f32x4*)(psg + 4 * jj);
; #pragma unroll
;                 for (int t = 0; t < 4; ++t) acc += *(const LAS f32x4*)(scr + (4 * jj + t) * 4) * a4[t]; }
	v_pk_fma_f32 v[76:77], v[88:89], v[78:79], v[76:77] op_sel_hi:[1,0,1]
	v_pk_fma_f32 v[96:97], v[90:91], v[78:79], v[96:97] op_sel_hi:[1,0,1]
	ds_read_b128 v[88:91], v139 offset:816
	v_mul_f32_e32 v78, v79, v99
	s_waitcnt lgkmcnt(0)
	v_pk_fma_f32 v[90:91], v[78:79], v[90:91], v[96:97] op_sel_hi:[0,1,1]
	v_pk_fma_f32 v[88:89], v[78:79], v[88:89], v[76:77] op_sel_hi:[0,1,1]
	ds_read_b128 v[76:79], v139 offset:832
	s_waitcnt lgkmcnt(0)
	v_pk_fma_f32 v[88:89], v[76:77], v[72:73], v[88:89] op_sel_hi:[1,0,1]
	v_pk_fma_f32 v[90:91], v[78:79], v[72:73], v[90:91] op_sel_hi:[1,0,1]
	ds_read_b128 v[76:79], v139 offset:848
	v_mul_f32_e32 v72, v73, v93
	s_waitcnt lgkmcnt(0)
	v_pk_fma_f32 v[90:91], v[78:79], v[72:73], v[90:91] op_sel_hi:[1,0,1]
	v_pk_fma_f32 v[72:73], v[76:77], v[72:73], v[88:89] op_sel_hi:[1,0,1]
	ds_read_b128 v[76:79], v139 offset:864
	s_waitcnt lgkmcnt(0)
	v_pk_fma_f32 v[72:73], v[76:77], v[74:75], v[72:73] op_sel_hi:[1,0,1]
	v_pk_fma_f32 v[88:89], v[78:79], v[74:75], v[90:91] op_sel_hi:[1,0,1]
	ds_read_b128 v[76:79], v139 offset:880
	v_mul_f32_e32 v74, v75, v95
	s_waitcnt lgkmcnt(0)
	v_pk_fma_f32 v[78:79], v[74:75], v[78:79], v[88:89] op_sel_hi:[0,1,1]
	v_pk_fma_f32 v[76:77], v[74:75], v[76:77], v[72:73] op_sel_hi:[0,1,1]
	ds_read_b128 v[72:75], v139 offset:896
	s_waitcnt lgkmcnt(0)
	v_pk_fma_f32 v[76:77], v[72:73], v[68:69], v[76:77] op_sel_hi:[1,0,1]
	v_pk_fma_f32 v[78:79], v[74:75], v[68:69], v[78:79] op_sel_hi:[1,0,1]
	ds_read_b128 v[72:75], v139 offset:912
	v_mul_f32_e32 v68, v69, v85
	s_waitcnt lgkmcnt(0)
	v_pk_fma_f32 v[78:79], v[74:75], v[68:69], v[78:79] op_sel_hi:[1,0,1]
	v_pk_fma_f32 v[68:69], v[72:73], v[68:69], v[76:77] op_sel_hi:[1,0,1]
	ds_read_b128 v[72:75], v139 offset:928
	s_waitcnt lgkmcnt(0)
	v_pk_fma_f32 v[68:69], v[72:73], v[70:71], v[68:69] op_sel_hi:[1,0,1]
	v_pk_fma_f32 v[76:77], v[74:75], v[70:71], v[78:79] op_sel_hi:[1,0,1]
	ds_read_b128 v[72:75], v139 offset:944
	v_mul_f32_e32 v70, v71, v87
	s_waitcnt lgkmcnt(0)
	v_pk_fma_f32 v[74:75], v[70:71], v[74:75], v[76:77] op_sel_hi:[0,1,1]
	v_pk_fma_f32 v[72:73], v[70:71], v[72:73], v[68:69] op_sel_hi:[0,1,1]
	ds_read_b128 v[68:71], v139 offset:960
	s_waitcnt lgkmcnt(0)
	v_pk_fma_f32 v[72:73], v[68:69], v[64:65], v[72:73] op_sel_hi:[1,0,1]
	v_pk_fma_f32 v[74:75], v[70:71], v[64:65], v[74:75] op_sel_hi:[1,0,1]
	ds_read_b128 v[68:71], v139 offset:976
	v_mul_f32_e32 v64, v65, v81
	s_waitcnt lgkmcnt(0)
	v_pk_fma_f32 v[74:75], v[70:71], v[64:65], v[74:75] op_sel_hi:[1,0,1]
	v_pk_fma_f32 v[64:65], v[68:69], v[64:65], v[72:73] op_sel_hi:[1,0,1]
	ds_read_b128 v[68:71], v139 offset:992
	s_waitcnt lgkmcnt(0)
	v_pk_fma_f32 v[64:65], v[68:69], v[66:67], v[64:65] op_sel_hi:[1,0,1]
	v_pk_fma_f32 v[72:73], v[70:71], v[66:67], v[74:75] op_sel_hi:[1,0,1]
	ds_read_b128 v[68:71], v139 offset:1008
	v_mul_f32_e32 v66, v67, v83
	s_waitcnt lgkmcnt(0)
	v_pk_fma_f32 v[76:77], v[66:67], v[70:71], v[72:73] op_sel_hi:[0,1,1]
	v_pk_fma_f32 v[78:79], v[66:67], v[68:69], v[64:65] op_sel_hi:[0,1,1]
	global_load_dwordx4 v[64:67], v113, s[62:63] offset:304
	global_load_dwordx4 v[68:71], v113, s[62:63] offset:288
	global_load_dwordx4 v[72:75], v113, s[62:63] offset:272
	global_load_dwordx4 v[80:83], v113, s[62:63] offset:256
	ds_read_b128 v[84:87], v139 offset:1024
	s_waitcnt vmcnt(3)
	v_mul_f32_e32 v48, v48, v64
	s_waitcnt vmcnt(2)
	v_mul_f32_e32 v52, v52, v68
	s_waitcnt vmcnt(1)
	v_mul_f32_e32 v56, v56, v72
	s_waitcnt vmcnt(0)
	v_mul_f32_e32 v60, v60, v80
	s_waitcnt lgkmcnt(0)
	v_pk_fma_f32 v[84:85], v[84:85], v[60:61], v[78:79] op_sel_hi:[1,0,1]
	v_pk_fma_f32 v[86:87], v[86:87], v[60:61], v[76:77] op_sel_hi:[1,0,1]
	ds_read_b128 v[76:79], v139 offset:1040
	v_mul_f32_e32 v60, v61, v81
	v_mul_f32_e32 v62, v62, v82
	v_mul_f32_e32 v58, v58, v74
	v_mul_f32_e32 v54, v54, v70
	s_waitcnt lgkmcnt(0)
	v_pk_fma_f32 v[80:81], v[78:79], v[60:61], v[86:87] op_sel_hi:[1,0,1]
	v_pk_fma_f32 v[60:61], v[76:77], v[60:61], v[84:85] op_sel_hi:[1,0,1]
	ds_read_b128 v[76:79], v139 offset:1056
	v_mul_f32_e32 v50, v50, v66
	s_waitcnt lgkmcnt(0)
	v_pk_fma_f32 v[60:61], v[76:77], v[62:63], v[60:61] op_sel_hi:[1,0,1]
	v_pk_fma_f32 v[80:81], v[78:79], v[62:63], v[80:81] op_sel_hi:[1,0,1]
	ds_read_b128 v[76:79], v139 offset:1072
	v_mul_f32_e32 v62, v63, v83
	s_waitcnt lgkmcnt(0)
	v_pk_fma_f32 v[78:79], v[62:63], v[78:79], v[80:81] op_sel_hi:[0,1,1]
	v_pk_fma_f32 v[76:77], v[62:63], v[76:77], v[60:61] op_sel_hi:[0,1,1]
	ds_read_b128 v[60:63], v139 offset:1088
	s_waitcnt lgkmcnt(0)
	v_pk_fma_f32 v[76:77], v[60:61], v[56:57], v[76:77] op_sel_hi:[1,0,1]
	v_pk_fma_f32 v[78:79], v[62:63], v[56:57], v[78:79] op_sel_hi:[1,0,1]
	ds_read_b128 v[60:63], v139 offset:1104
	v_mul_f32_e32 v56, v57, v73
	s_waitcnt lgkmcnt(0)
	v_pk_fma_f32 v[72:73], v[62:63], v[56:57], v[78:79] op_sel_hi:[1,0,1]
	v_pk_fma_f32 v[56:57], v[60:61], v[56:57], v[76:77] op_sel_hi:[1,0,1]
	ds_read_b128 v[60:63], v139 offset:1120
	s_waitcnt lgkmcnt(0)
	v_pk_fma_f32 v[56:57], v[60:61], v[58:59], v[56:57] op_sel_hi:[1,0,1]
	v_pk_fma_f32 v[72:73], v[62:63], v[58:59], v[72:73] op_sel_hi:[1,0,1]
	ds_read_b128 v[60:63], v139 offset:1136
	v_mul_f32_e32 v58, v59, v75
	s_waitcnt lgkmcnt(0)
	v_pk_fma_f32 v[62:63], v[58:59], v[62:63], v[72:73] op_sel_hi:[0,1,1]
	v_pk_fma_f32 v[60:61], v[58:59], v[60:61], v[56:57] op_sel_hi:[0,1,1]
	ds_read_b128 v[56:59], v139 offset:1152
	s_waitcnt lgkmcnt(0)
	v_pk_fma_f32 v[60:61], v[56:57], v[52:53], v[60:61] op_sel_hi:[1,0,1]
	v_pk_fma_f32 v[62:63], v[58:59], v[52:53], v[62:63] op_sel_hi:[1,0,1]
	ds_read_b128 v[56:59], v139 offset:1168
	v_mul_f32_e32 v52, v53, v69
	s_waitcnt lgkmcnt(0)
; #define LAS __attribute__((address_space(3)))
; __device__ __forceinline__ void prep_phase(const Params& p, int l, LAS unsigned char* lds) {
;     ...
;             for (int jj = 0; jj < 32; ++jj) { const f32x4 a4 = pwv[jj] * *(const f32x4*)(psg + 4 * jj);
; #pragma unroll
;                 for (int t = 0; t < 4; ++t) acc += *(const LAS f32x4*)(scr + (4 * jj + t) * 4) * a4[t]; }
	v_pk_fma_f32 v[62:63], v[58:59], v[52:53], v[62:63] op_sel_hi:[1,0,1]
	v_pk_fma_f32 v[52:53], v[56:57], v[52:53], v[60:61] op_sel_hi:[1,0,1]
	ds_read_b128 v[56:59], v139 offset:1184
	s_waitcnt lgkmcnt(0)
	v_pk_fma_f32 v[52:53], v[56:57], v[54:55], v[52:53] op_sel_hi:[1,0,1]
	v_pk_fma_f32 v[60:61], v[58:59], v[54:55], v[62:63] op_sel_hi:[1,0,1]
	ds_read_b128 v[56:59], v139 offset:1200
	v_mul_f32_e32 v54, v55, v71
	s_waitcnt lgkmcnt(0)
	v_pk_fma_f32 v[58:59], v[54:55], v[58:59], v[60:61] op_sel_hi:[0,1,1]
	v_pk_fma_f32 v[56:57], v[54:55], v[56:57], v[52:53] op_sel_hi:[0,1,1]
	ds_read_b128 v[52:55], v139 offset:1216
	s_waitcnt lgkmcnt(0)
	v_pk_fma_f32 v[56:57], v[52:53], v[48:49], v[56:57] op_sel_hi:[1,0,1]
	v_pk_fma_f32 v[58:59], v[54:55], v[48:49], v[58:59] op_sel_hi:[1,0,1]
	ds_read_b128 v[52:55], v139 offset:1232
	v_mul_f32_e32 v48, v49, v65
	s_waitcnt lgkmcnt(0)
	v_pk_fma_f32 v[58:59], v[54:55], v[48:49], v[58:59] op_sel_hi:[1,0,1]
	v_pk_fma_f32 v[48:49], v[52:53], v[48:49], v[56:57] op_sel_hi:[1,0,1]
	ds_read_b128 v[52:55], v139 offset:1248
	s_waitcnt lgkmcnt(0)
	v_pk_fma_f32 v[48:49], v[52:53], v[50:51], v[48:49] op_sel_hi:[1,0,1]
	v_pk_fma_f32 v[56:57], v[54:55], v[50:51], v[58:59] op_sel_hi:[1,0,1]
	ds_read_b128 v[52:55], v139 offset:1264
	v_mul_f32_e32 v50, v51, v67
	s_waitcnt lgkmcnt(0)
	v_pk_fma_f32 v[60:61], v[50:51], v[54:55], v[56:57] op_sel_hi:[0,1,1]
	v_pk_fma_f32 v[62:63], v[50:51], v[52:53], v[48:49] op_sel_hi:[0,1,1]
	global_load_dwordx4 v[48:51], v113, s[62:63] offset:368
	global_load_dwordx4 v[52:55], v113, s[62:63] offset:352
	global_load_dwordx4 v[56:59], v113, s[62:63] offset:336
	global_load_dwordx4 v[64:67], v113, s[62:63] offset:320
	ds_read_b128 v[68:71], v139 offset:1280
	s_waitcnt vmcnt(3)
	v_mul_f32_e32 v32, v32, v48
	s_waitcnt vmcnt(2)
	v_mul_f32_e32 v36, v36, v52
	s_waitcnt vmcnt(1)
	v_mul_f32_e32 v40, v40, v56
	s_waitcnt vmcnt(0)
	v_mul_f32_e32 v44, v44, v64
	s_waitcnt lgkmcnt(0)
	v_pk_fma_f32 v[68:69], v[68:69], v[44:45], v[62:63] op_sel_hi:[1,0,1]
	v_pk_fma_f32 v[70:71], v[70:71], v[44:45], v[60:61] op_sel_hi:[1,0,1]
	ds_read_b128 v[60:63], v139 offset:1296
	v_mul_f32_e32 v44, v45, v65
	v_mul_f32_e32 v46, v46, v66
	v_mul_f32_e32 v42, v42, v58
	v_mul_f32_e32 v38, v38, v54
	s_waitcnt lgkmcnt(0)
	v_pk_fma_f32 v[64:65], v[62:63], v[44:45], v[70:71] op_sel_hi:[1,0,1]
	v_pk_fma_f32 v[44:45], v[60:61], v[44:45], v[68:69] op_sel_hi:[1,0,1]
	ds_read_b128 v[60:63], v139 offset:1312
	v_mul_f32_e32 v34, v34, v50
	s_waitcnt lgkmcnt(0)
	v_pk_fma_f32 v[44:45], v[60:61], v[46:47], v[44:45] op_sel_hi:[1,0,1]
	v_pk_fma_f32 v[64:65], v[62:63], v[46:47], v[64:65] op_sel_hi:[1,0,1]
	ds_read_b128 v[60:63], v139 offset:1328
	v_mul_f32_e32 v46, v47, v67
	s_waitcnt lgkmcnt(0)
	v_pk_fma_f32 v[62:63], v[46:47], v[62:63], v[64:65] op_sel_hi:[0,1,1]
	v_pk_fma_f32 v[60:61], v[46:47], v[60:61], v[44:45] op_sel_hi:[0,1,1]
	ds_read_b128 v[44:47], v139 offset:1344
	s_waitcnt lgkmcnt(0)
	v_pk_fma_f32 v[60:61], v[44:45], v[40:41], v[60:61] op_sel_hi:[1,0,1]
	v_pk_fma_f32 v[62:63], v[46:47], v[40:41], v[62:63] op_sel_hi:[1,0,1]
	ds_read_b128 v[44:47], v139 offset:1360
	v_mul_f32_e32 v40, v41, v57
	s_waitcnt lgkmcnt(0)
	v_pk_fma_f32 v[56:57], v[46:47], v[40:41], v[62:63] op_sel_hi:[1,0,1]
	v_pk_fma_f32 v[40:41], v[44:45], v[40:41], v[60:61] op_sel_hi:[1,0,1]
	ds_read_b128 v[44:47], v139 offset:1376
	s_waitcnt lgkmcnt(0)
	v_pk_fma_f32 v[40:41], v[44:45], v[42:43], v[40:41] op_sel_hi:[1,0,1]
	v_pk_fma_f32 v[56:57], v[46:47], v[42:43], v[56:57] op_sel_hi:[1,0,1]
	ds_read_b128 v[44:47], v139 offset:1392
	v_mul_f32_e32 v42, v43, v59
	s_waitcnt lgkmcnt(0)
	v_pk_fma_f32 v[46:47], v[42:43], v[46:47], v[56:57] op_sel_hi:[0,1,1]
	v_pk_fma_f32 v[44:45], v[42:43], v[44:45], v[40:41] op_sel_hi:[0,1,1]
	ds_read_b128 v[40:43], v139 offset:1408
	s_waitcnt lgkmcnt(0)
	v_pk_fma_f32 v[44:45], v[40:41], v[36:37], v[44:45] op_sel_hi:[1,0,1]
	v_pk_fma_f32 v[46:47], v[42:43], v[36:37], v[46:47] op_sel_hi:[1,0,1]
	ds_read_b128 v[40:43], v139 offset:1424
	v_mul_f32_e32 v36, v37, v53
	s_waitcnt lgkmcnt(0)
	v_pk_fma_f32 v[46:47], v[42:43], v[36:37], v[46:47] op_sel_hi:[1,0,1]
	v_pk_fma_f32 v[36:37], v[40:41], v[36:37], v[44:45] op_sel_hi:[1,0,1]
	ds_read_b128 v[40:43], v139 offset:1440
	s_waitcnt lgkmcnt(0)
	v_pk_fma_f32 v[36:37], v[40:41], v[38:39], v[36:37] op_sel_hi:[1,0,1]
	v_pk_fma_f32 v[44:45], v[42:43], v[38:39], v[46:47] op_sel_hi:[1,0,1]
	ds_read_b128 v[40:43], v139 offset:1456
	v_mul_f32_e32 v38, v39, v55
	s_waitcnt lgkmcnt(0)
	v_pk_fma_f32 v[42:43], v[38:39], v[42:43], v[44:45] op_sel_hi:[0,1,1]
	v_pk_fma_f32 v[40:41], v[38:39], v[40:41], v[36:37] op_sel_hi:[0,1,1]
	ds_read_b128 v[36:39], v139 offset:1472
	s_waitcnt lgkmcnt(0)
	v_pk_fma_f32 v[40:41], v[36:37], v[32:33], v[40:41] op_sel_hi:[1,0,1]
	v_pk_fma_f32 v[42:43], v[38:39], v[32:33], v[42:43] op_sel_hi:[1,0,1]
	ds_read_b128 v[36:39], v139 offset:1488
	v_mul_f32_e32 v32, v33, v49
	s_waitcnt lgkmcnt(0)
	v_pk_fma_f32 v[42:43], v[38:39], v[32:33], v[42:43] op_sel_hi:[1,0,1]
	v_pk_fma_f32 v[32:33], v[36:37], v[32:33], v[40:41] op_sel_hi:[1,0,1]
	ds_read_b128 v[36:39], v139 offset:1504
	s_waitcnt lgkmcnt(0)
	v_pk_fma_f32 v[32:33], v[36:37], v[34:35], v[32:33] op_sel_hi:[1,0,1]
	v_pk_fma_f32 v[40:41], v[38:39], v[34:35], v[42:43] op_sel_hi:[1,0,1]
	ds_read_b128 v[36:39], v139 offset:1520
	v_mul_f32_e32 v34, v35, v51
	s_waitcnt lgkmcnt(0)
	v_pk_fma_f32 v[44:45], v[34:35], v[38:39], v[40:41] op_sel_hi:[0,1,1]
	v_pk_fma_f32 v[46:47], v[34:35], v[36:37], v[32:33] op_sel_hi:[0,1,1]
	global_load_dwordx4 v[32:35], v113, s[62:63] offset:432
	global_load_dwordx4 v[36:39], v113, s[62:63] offset:416
	global_load_dwordx4 v[40:43], v113, s[62:63] offset:400
	global_load_dwordx4 v[48:51], v113, s[62:63] offset:384
	ds_read_b128 v[52:55], v139 offset:1536
	s_waitcnt vmcnt(3)
; #define LAS __attribute__((address_space(3)))
; __device__ __forceinline__ void prep_phase(const Params& p, int l, LAS unsigned char* lds) {
;     ...
;             for (int jj = 0; jj < 32; ++jj) { const f32x4 a4 = pwv[jj] * *(const f32x4*)(psg + 4 * jj);
; #pragma unroll
;                 for (int t = 0; t < 4; ++t) acc += *(const LAS f32x4*)(scr + (4 * jj + t) * 4) * a4[t]; }
	v_mul_f32_e32 v16, v16, v32
	s_waitcnt vmcnt(2)
	v_mul_f32_e32 v20, v20, v36
	s_waitcnt vmcnt(1)
	v_mul_f32_e32 v24, v24, v40
	s_waitcnt vmcnt(0)
	v_mul_f32_e32 v28, v28, v48
	s_waitcnt lgkmcnt(0)
	v_pk_fma_f32 v[52:53], v[52:53], v[28:29], v[46:47] op_sel_hi:[1,0,1]
	v_pk_fma_f32 v[54:55], v[54:55], v[28:29], v[44:45] op_sel_hi:[1,0,1]
	ds_read_b128 v[44:47], v139 offset:1552
	v_mul_f32_e32 v28, v29, v49
	v_mul_f32_e32 v30, v30, v50
	v_mul_f32_e32 v26, v26, v42
	v_mul_f32_e32 v22, v22, v38
	s_waitcnt lgkmcnt(0)
	v_pk_fma_f32 v[48:49], v[46:47], v[28:29], v[54:55] op_sel_hi:[1,0,1]
	v_pk_fma_f32 v[28:29], v[44:45], v[28:29], v[52:53] op_sel_hi:[1,0,1]
	ds_read_b128 v[44:47], v139 offset:1568
	v_mul_f32_e32 v18, v18, v34
	s_waitcnt lgkmcnt(0)
	v_pk_fma_f32 v[28:29], v[44:45], v[30:31], v[28:29] op_sel_hi:[1,0,1]
	v_pk_fma_f32 v[48:49], v[46:47], v[30:31], v[48:49] op_sel_hi:[1,0,1]
	ds_read_b128 v[44:47], v139 offset:1584
	v_mul_f32_e32 v30, v31, v51
	s_waitcnt lgkmcnt(0)
	v_pk_fma_f32 v[46:47], v[30:31], v[46:47], v[48:49] op_sel_hi:[0,1,1]
	v_pk_fma_f32 v[44:45], v[30:31], v[44:45], v[28:29] op_sel_hi:[0,1,1]
	ds_read_b128 v[28:31], v139 offset:1600
	s_waitcnt lgkmcnt(0)
	v_pk_fma_f32 v[44:45], v[28:29], v[24:25], v[44:45] op_sel_hi:[1,0,1]
	v_pk_fma_f32 v[46:47], v[30:31], v[24:25], v[46:47] op_sel_hi:[1,0,1]
	ds_read_b128 v[28:31], v139 offset:1616
	v_mul_f32_e32 v24, v25, v41
	s_waitcnt lgkmcnt(0)
	v_pk_fma_f32 v[40:41], v[30:31], v[24:25], v[46:47] op_sel_hi:[1,0,1]
	v_pk_fma_f32 v[24:25], v[28:29], v[24:25], v[44:45] op_sel_hi:[1,0,1]
	ds_read_b128 v[28:31], v139 offset:1632
	s_waitcnt lgkmcnt(0)
	v_pk_fma_f32 v[24:25], v[28:29], v[26:27], v[24:25] op_sel_hi:[1,0,1]
	v_pk_fma_f32 v[40:41], v[30:31], v[26:27], v[40:41] op_sel_hi:[1,0,1]
	ds_read_b128 v[28:31], v139 offset:1648
	v_mul_f32_e32 v26, v27, v43
	s_waitcnt lgkmcnt(0)
	v_pk_fma_f32 v[30:31], v[26:27], v[30:31], v[40:41] op_sel_hi:[0,1,1]
	v_pk_fma_f32 v[28:29], v[26:27], v[28:29], v[24:25] op_sel_hi:[0,1,1]
	ds_read_b128 v[24:27], v139 offset:1664
	s_waitcnt lgkmcnt(0)
	v_pk_fma_f32 v[28:29], v[24:25], v[20:21], v[28:29] op_sel_hi:[1,0,1]
	v_pk_fma_f32 v[30:31], v[26:27], v[20:21], v[30:31] op_sel_hi:[1,0,1]
	ds_read_b128 v[24:27], v139 offset:1680
	v_mul_f32_e32 v20, v21, v37
	s_waitcnt lgkmcnt(0)
	v_pk_fma_f32 v[30:31], v[26:27], v[20:21], v[30:31] op_sel_hi:[1,0,1]
	v_pk_fma_f32 v[20:21], v[24:25], v[20:21], v[28:29] op_sel_hi:[1,0,1]
	ds_read_b128 v[24:27], v139 offset:1696
	s_waitcnt lgkmcnt(0)
	v_pk_fma_f32 v[20:21], v[24:25], v[22:23], v[20:21] op_sel_hi:[1,0,1]
	v_pk_fma_f32 v[28:29], v[26:27], v[22:23], v[30:31] op_sel_hi:[1,0,1]
	ds_read_b128 v[24:27], v139 offset:1712
	v_mul_f32_e32 v22, v23, v39
	s_waitcnt lgkmcnt(0)
	v_pk_fma_f32 v[26:27], v[22:23], v[26:27], v[28:29] op_sel_hi:[0,1,1]
	v_pk_fma_f32 v[24:25], v[22:23], v[24:25], v[20:21] op_sel_hi:[0,1,1]
	ds_read_b128 v[20:23], v139 offset:1728
	s_waitcnt lgkmcnt(0)
	v_pk_fma_f32 v[24:25], v[20:21], v[16:17], v[24:25] op_sel_hi:[1,0,1]
	v_pk_fma_f32 v[26:27], v[22:23], v[16:17], v[26:27] op_sel_hi:[1,0,1]
	ds_read_b128 v[20:23], v139 offset:1744
	v_mul_f32_e32 v16, v17, v33
	s_waitcnt lgkmcnt(0)
	v_pk_fma_f32 v[26:27], v[22:23], v[16:17], v[26:27] op_sel_hi:[1,0,1]
	v_pk_fma_f32 v[16:17], v[20:21], v[16:17], v[24:25] op_sel_hi:[1,0,1]
	ds_read_b128 v[20:23], v139 offset:1760
	s_waitcnt lgkmcnt(0)
	v_pk_fma_f32 v[16:17], v[20:21], v[18:19], v[16:17] op_sel_hi:[1,0,1]
	v_pk_fma_f32 v[24:25], v[22:23], v[18:19], v[26:27] op_sel_hi:[1,0,1]
	ds_read_b128 v[20:23], v139 offset:1776
	v_mul_f32_e32 v18, v19, v35
	s_waitcnt lgkmcnt(0)
	v_pk_fma_f32 v[32:33], v[18:19], v[22:23], v[24:25] op_sel_hi:[0,1,1]
	v_pk_fma_f32 v[34:35], v[18:19], v[20:21], v[16:17] op_sel_hi:[0,1,1]
	global_load_dwordx4 v[16:19], v113, s[62:63] offset:496
	global_load_dwordx4 v[20:23], v113, s[62:63] offset:480
	global_load_dwordx4 v[24:27], v113, s[62:63] offset:464
	global_load_dwordx4 v[28:31], v113, s[62:63] offset:448
	ds_read_b128 v[36:39], v139 offset:1792
	s_waitcnt vmcnt(3)
	v_mul_f32_e32 v0, v0, v16
	s_waitcnt vmcnt(2)
	v_mul_f32_e32 v4, v4, v20
	s_waitcnt vmcnt(1)
; #define LAS __attribute__((address_space(3)))
; __device__ __forceinline__ bf16_t f2bf(float f) { return (bf16_t)(pk2(f, 0.f) & 0xffffu); }
; __device__ __forceinline__ void prep_phase(const Params& p, int l, LAS unsigned char* lds) {
;     ...
;             for (int jj = 0; jj < 32; ++jj) { const f32x4 a4 = pwv[jj] * *(const f32x4*)(psg + 4 * jj);
; #pragma unroll
;                 for (int t = 0; t < 4; ++t) acc += *(const LAS f32x4*)(scr + (4 * jj + t) * 4) * a4[t]; }
; #pragma unroll
;             for (int dd = 0; dd < 4; ++dd) WuaT[(size_t)(d0 + dd) * 1024 + 512 + g * 128 + c] = f2bf(acc[dd]);
;             asm volatile("s_waitcnt lgkmcnt(0)" ::: "memory");
	v_mul_f32_e32 v8, v8, v24
	s_waitcnt vmcnt(0)
	v_mul_f32_e32 v12, v12, v28
	s_waitcnt lgkmcnt(0)
	v_pk_fma_f32 v[36:37], v[36:37], v[12:13], v[34:35] op_sel_hi:[1,0,1]
	v_pk_fma_f32 v[38:39], v[38:39], v[12:13], v[32:33] op_sel_hi:[1,0,1]
	ds_read_b128 v[32:35], v139 offset:1808
	v_mul_f32_e32 v12, v13, v29
	v_mul_f32_e32 v14, v14, v30
	v_mul_f32_e32 v10, v10, v26
	v_mul_f32_e32 v6, v6, v22
	s_waitcnt lgkmcnt(0)
	v_pk_fma_f32 v[28:29], v[34:35], v[12:13], v[38:39] op_sel_hi:[1,0,1]
	v_pk_fma_f32 v[12:13], v[32:33], v[12:13], v[36:37] op_sel_hi:[1,0,1]
	ds_read_b128 v[32:35], v139 offset:1824
	v_mul_f32_e32 v2, v2, v18
	s_waitcnt lgkmcnt(0)
	v_pk_fma_f32 v[12:13], v[32:33], v[14:15], v[12:13] op_sel_hi:[1,0,1]
	v_pk_fma_f32 v[28:29], v[34:35], v[14:15], v[28:29] op_sel_hi:[1,0,1]
	ds_read_b128 v[32:35], v139 offset:1840
	v_mul_f32_e32 v14, v15, v31
	s_waitcnt lgkmcnt(0)
	v_pk_fma_f32 v[28:29], v[14:15], v[34:35], v[28:29] op_sel_hi:[0,1,1]
	v_pk_fma_f32 v[30:31], v[14:15], v[32:33], v[12:13] op_sel_hi:[0,1,1]
	ds_read_b128 v[12:15], v139 offset:1856
	s_waitcnt lgkmcnt(0)
	v_pk_fma_f32 v[30:31], v[12:13], v[8:9], v[30:31] op_sel_hi:[1,0,1]
	v_pk_fma_f32 v[28:29], v[14:15], v[8:9], v[28:29] op_sel_hi:[1,0,1]
	ds_read_b128 v[12:15], v139 offset:1872
	v_mul_f32_e32 v8, v9, v25
	s_waitcnt lgkmcnt(0)
	v_pk_fma_f32 v[24:25], v[14:15], v[8:9], v[28:29] op_sel_hi:[1,0,1]
	v_pk_fma_f32 v[8:9], v[12:13], v[8:9], v[30:31] op_sel_hi:[1,0,1]
	ds_read_b128 v[12:15], v139 offset:1888
	s_waitcnt lgkmcnt(0)
	v_pk_fma_f32 v[8:9], v[12:13], v[10:11], v[8:9] op_sel_hi:[1,0,1]
	v_pk_fma_f32 v[24:25], v[14:15], v[10:11], v[24:25] op_sel_hi:[1,0,1]
	ds_read_b128 v[12:15], v139 offset:1904
	v_mul_f32_e32 v10, v11, v27
	s_waitcnt lgkmcnt(0)
	v_pk_fma_f32 v[14:15], v[10:11], v[14:15], v[24:25] op_sel_hi:[0,1,1]
	v_pk_fma_f32 v[12:13], v[10:11], v[12:13], v[8:9] op_sel_hi:[0,1,1]
	ds_read_b128 v[8:11], v139 offset:1920
	s_waitcnt lgkmcnt(0)
	v_pk_fma_f32 v[12:13], v[8:9], v[4:5], v[12:13] op_sel_hi:[1,0,1]
	v_pk_fma_f32 v[14:15], v[10:11], v[4:5], v[14:15] op_sel_hi:[1,0,1]
	ds_read_b128 v[8:11], v139 offset:1936
	v_mul_f32_e32 v4, v5, v21
	s_waitcnt lgkmcnt(0)
	v_pk_fma_f32 v[14:15], v[10:11], v[4:5], v[14:15] op_sel_hi:[1,0,1]
	v_pk_fma_f32 v[4:5], v[8:9], v[4:5], v[12:13] op_sel_hi:[1,0,1]
	ds_read_b128 v[8:11], v139 offset:1952
	s_waitcnt lgkmcnt(0)
	v_pk_fma_f32 v[4:5], v[8:9], v[6:7], v[4:5] op_sel_hi:[1,0,1]
	v_pk_fma_f32 v[12:13], v[10:11], v[6:7], v[14:15] op_sel_hi:[1,0,1]
	ds_read_b128 v[8:11], v139 offset:1968
	v_mul_f32_e32 v6, v7, v23
	s_waitcnt lgkmcnt(0)
	v_pk_fma_f32 v[10:11], v[6:7], v[10:11], v[12:13] op_sel_hi:[0,1,1]
	v_pk_fma_f32 v[8:9], v[6:7], v[8:9], v[4:5] op_sel_hi:[0,1,1]
	ds_read_b128 v[4:7], v139 offset:1984
	s_waitcnt lgkmcnt(0)
	v_pk_fma_f32 v[8:9], v[4:5], v[0:1], v[8:9] op_sel_hi:[1,0,1]
	v_pk_fma_f32 v[10:11], v[6:7], v[0:1], v[10:11] op_sel_hi:[1,0,1]
	ds_read_b128 v[4:7], v139 offset:2000
	v_mul_f32_e32 v0, v1, v17
	s_waitcnt lgkmcnt(0)
	v_pk_fma_f32 v[10:11], v[6:7], v[0:1], v[10:11] op_sel_hi:[1,0,1]
	v_pk_fma_f32 v[0:1], v[4:5], v[0:1], v[8:9] op_sel_hi:[1,0,1]
	ds_read_b128 v[4:7], v139 offset:2016
	s_waitcnt lgkmcnt(0)
	v_pk_fma_f32 v[0:1], v[4:5], v[2:3], v[0:1] op_sel_hi:[1,0,1]
	v_pk_fma_f32 v[8:9], v[6:7], v[2:3], v[10:11] op_sel_hi:[1,0,1]
	ds_read_b128 v[4:7], v139 offset:2032
	v_mul_f32_e32 v2, v3, v19
	s_waitcnt lgkmcnt(0)
	v_pk_fma_f32 v[0:1], v[2:3], v[4:5], v[0:1] op_sel_hi:[0,1,1]
	v_cvt_pk_bf16_f32 v0, v0, s0
	s_lshl_b32 s0, s12, 11
	s_add_u32 s12, s26, s0
	s_addc_u32 s13, s33, 0
	s_lshl_b64 s[0:1], s[54:55], 1
	s_add_u32 s0, s12, s0
	s_addc_u32 s1, s13, s1
	v_pk_fma_f32 v[6:7], v[2:3], v[6:7], v[8:9] op_sel_hi:[0,1,1]
	v_lshl_add_u64 v[2:3], s[0:1], 0, v[112:113]
	global_store_short v112, v0, s[0:1] offset:1024
	v_cvt_pk_bf16_f32 v0, v1, s0
	global_store_short v112, v0, s[0:1] offset:3072
	v_add_co_u32_e32 v0, vcc, 0x1000, v2
	v_cvt_pk_bf16_f32 v4, v6, s0
	s_nop 0
	v_addc_co_u32_e32 v1, vcc, 0, v3, vcc
	v_cvt_pk_bf16_f32 v2, v7, s0
	global_store_short v[0:1], v4, off offset:1024
	global_store_short v[0:1], v2, off offset:3072
	s_waitcnt lgkmcnt(0)
	s_branch .LBB0_16
